# P1 key block-mean path: DPP row butterfly instead of 64 serial ds_bpermute round trips per unit
# baseline (speedup 1.0000x reference)
.LBB0_192:
	s_ashr_i32 s5, s4, 31
	s_lshl_b64 s[6:7], s[4:5], 12
	s_add_u32 s5, s80, s6
	s_addc_u32 s30, s81, s7
	s_lshl_b64 s[6:7], s[8:9], 2
	s_add_u32 s6, s5, s6
	s_addc_u32 s7, s30, s7
	v_lshlrev_b32_e32 v148, 3, v163
	v_ashrrev_i32_e32 v149, 31, v148
	v_lshl_add_u64 v[148:149], v[148:149], 2, s[6:7]
	v_cmp_eq_u32_e32 vcc, 0, v138
	v_add_f32_e32 v154, 0, v126
	v_add_f32_e32 v155, 0, v127
	v_add_f32_e32 v154, v154, v110
	v_add_f32_e32 v155, v155, v111
	v_add_f32_e32 v154, v154, v94
	v_add_f32_e32 v155, v155, v95
	v_add_f32_e32 v154, v154, v78
	v_add_f32_e32 v155, v155, v79
	v_add_f32_e32 v154, v154, v62
	v_add_f32_e32 v155, v155, v63
	v_add_f32_e32 v154, v154, v46
	v_add_f32_e32 v155, v155, v47
	v_add_f32_e32 v154, v154, v30
	v_add_f32_e32 v155, v155, v31
	v_add_f32_e32 v154, v154, v14
	v_add_f32_e32 v155, v155, v15
	s_nop 0
	v_add_f32_dpp v154, v154, v154 quad_perm:[1,0,3,2] row_mask:0xf bank_mask:0xf
	v_add_f32_dpp v155, v155, v155 quad_perm:[1,0,3,2] row_mask:0xf bank_mask:0xf
	s_nop 0
	v_add_f32_dpp v154, v154, v154 quad_perm:[2,3,0,1] row_mask:0xf bank_mask:0xf
	v_add_f32_dpp v155, v155, v155 quad_perm:[2,3,0,1] row_mask:0xf bank_mask:0xf
	s_nop 0
	v_add_f32_dpp v154, v154, v154 row_half_mirror row_mask:0xf bank_mask:0xf
	v_add_f32_dpp v155, v155, v155 row_half_mirror row_mask:0xf bank_mask:0xf
	s_nop 0
	v_add_f32_dpp v154, v154, v154 row_mirror row_mask:0xf bank_mask:0xf
	v_add_f32_dpp v155, v155, v155 row_mirror row_mask:0xf bank_mask:0xf
	s_and_saveexec_b64 s[62:63], vcc
	global_store_dword v[148:149], v154, off
	s_bitset1_b32 s98, 0
	global_store_dword v[148:149], v155, off offset:4
	s_bitset1_b32 s98, 1
	s_or_b64 exec, exec, s[62:63]
	v_add_f32_e32 v154, 0, v128
	v_add_f32_e32 v155, 0, v129
	v_add_f32_e32 v154, v154, v112
	v_add_f32_e32 v155, v155, v113
	v_add_f32_e32 v154, v154, v96
	v_add_f32_e32 v155, v155, v97
	v_add_f32_e32 v154, v154, v80
	v_add_f32_e32 v155, v155, v81
	v_add_f32_e32 v154, v154, v64
	v_add_f32_e32 v155, v155, v65
	v_add_f32_e32 v154, v154, v48
	v_add_f32_e32 v155, v155, v49
	v_add_f32_e32 v154, v154, v32
	v_add_f32_e32 v155, v155, v33
	v_add_f32_e32 v154, v154, v16
	v_add_f32_e32 v155, v155, v17
	s_nop 0
	v_add_f32_dpp v154, v154, v154 quad_perm:[1,0,3,2] row_mask:0xf bank_mask:0xf
	v_add_f32_dpp v155, v155, v155 quad_perm:[1,0,3,2] row_mask:0xf bank_mask:0xf
	s_nop 0
	v_add_f32_dpp v154, v154, v154 quad_perm:[2,3,0,1] row_mask:0xf bank_mask:0xf
	v_add_f32_dpp v155, v155, v155 quad_perm:[2,3,0,1] row_mask:0xf bank_mask:0xf
	s_nop 0
	v_add_f32_dpp v154, v154, v154 row_half_mirror row_mask:0xf bank_mask:0xf
	v_add_f32_dpp v155, v155, v155 row_half_mirror row_mask:0xf bank_mask:0xf
	s_nop 0
	v_add_f32_dpp v154, v154, v154 row_mirror row_mask:0xf bank_mask:0xf
	v_add_f32_dpp v155, v155, v155 row_mirror row_mask:0xf bank_mask:0xf
	s_and_saveexec_b64 s[62:63], vcc
	global_store_dword v[148:149], v154, off offset:8
	s_bitset1_b32 s98, 2
	global_store_dword v[148:149], v155, off offset:12
	s_bitset1_b32 s98, 3
	s_or_b64 exec, exec, s[62:63]
	v_add_f32_e32 v154, 0, v122
	v_add_f32_e32 v155, 0, v123
	v_add_f32_e32 v154, v154, v106
	v_add_f32_e32 v155, v155, v107
	v_add_f32_e32 v154, v154, v90
	v_add_f32_e32 v155, v155, v91
	v_add_f32_e32 v154, v154, v74
	v_add_f32_e32 v155, v155, v75
	v_add_f32_e32 v154, v154, v58
	v_add_f32_e32 v155, v155, v59
	v_add_f32_e32 v154, v154, v42
	v_add_f32_e32 v155, v155, v43
	v_add_f32_e32 v154, v154, v26
	v_add_f32_e32 v155, v155, v27
	v_add_f32_e32 v154, v154, v10
	v_add_f32_e32 v155, v155, v11
	s_nop 0
	v_add_f32_dpp v154, v154, v154 quad_perm:[1,0,3,2] row_mask:0xf bank_mask:0xf
	v_add_f32_dpp v155, v155, v155 quad_perm:[1,0,3,2] row_mask:0xf bank_mask:0xf
	s_nop 0
	v_add_f32_dpp v154, v154, v154 quad_perm:[2,3,0,1] row_mask:0xf bank_mask:0xf
	v_add_f32_dpp v155, v155, v155 quad_perm:[2,3,0,1] row_mask:0xf bank_mask:0xf
	s_nop 0
	v_add_f32_dpp v154, v154, v154 row_half_mirror row_mask:0xf bank_mask:0xf
	v_add_f32_dpp v155, v155, v155 row_half_mirror row_mask:0xf bank_mask:0xf
	s_nop 0
	v_add_f32_dpp v154, v154, v154 row_mirror row_mask:0xf bank_mask:0xf
	v_add_f32_dpp v155, v155, v155 row_mirror row_mask:0xf bank_mask:0xf
	s_and_saveexec_b64 s[62:63], vcc
	global_store_dword v[148:149], v154, off offset:16
	s_bitset1_b32 s98, 4
	global_store_dword v[148:149], v155, off offset:20
	s_bitset1_b32 s98, 5
	s_or_b64 exec, exec, s[62:63]
	v_add_f32_e32 v154, 0, v124
	v_add_f32_e32 v155, 0, v125
	v_add_f32_e32 v154, v154, v108
	v_add_f32_e32 v155, v155, v109
	v_add_f32_e32 v154, v154, v92
	v_add_f32_e32 v155, v155, v93
	v_add_f32_e32 v154, v154, v76
	v_add_f32_e32 v155, v155, v77
	v_add_f32_e32 v154, v154, v60
	v_add_f32_e32 v155, v155, v61
	v_add_f32_e32 v154, v154, v44
	v_add_f32_e32 v155, v155, v45
	v_add_f32_e32 v154, v154, v28
	v_add_f32_e32 v155, v155, v29
	v_add_f32_e32 v154, v154, v12
	v_add_f32_e32 v155, v155, v13
	s_nop 0
	v_add_f32_dpp v154, v154, v154 quad_perm:[1,0,3,2] row_mask:0xf bank_mask:0xf
	v_add_f32_dpp v155, v155, v155 quad_perm:[1,0,3,2] row_mask:0xf bank_mask:0xf
	s_nop 0
	v_add_f32_dpp v154, v154, v154 quad_perm:[2,3,0,1] row_mask:0xf bank_mask:0xf
	v_add_f32_dpp v155, v155, v155 quad_perm:[2,3,0,1] row_mask:0xf bank_mask:0xf
	s_nop 0
	v_add_f32_dpp v154, v154, v154 row_half_mirror row_mask:0xf bank_mask:0xf
	v_add_f32_dpp v155, v155, v155 row_half_mirror row_mask:0xf bank_mask:0xf
	s_nop 0
	v_add_f32_dpp v154, v154, v154 row_mirror row_mask:0xf bank_mask:0xf
	v_add_f32_dpp v155, v155, v155 row_mirror row_mask:0xf bank_mask:0xf
	s_and_saveexec_b64 s[62:63], vcc
	global_store_dword v[148:149], v154, off offset:24
	s_bitset1_b32 s98, 6
	global_store_dword v[148:149], v155, off offset:28
	s_bitset1_b32 s98, 7
	s_or_b64 exec, exec, s[62:63]
	v_add_f32_e32 v154, 0, v118
	v_add_f32_e32 v155, 0, v119
	v_add_f32_e32 v154, v154, v102
	v_add_f32_e32 v155, v155, v103
	v_add_f32_e32 v154, v154, v86
	v_add_f32_e32 v155, v155, v87
	v_add_f32_e32 v154, v154, v70
	v_add_f32_e32 v155, v155, v71
	v_add_f32_e32 v154, v154, v54
	v_add_f32_e32 v155, v155, v55
	v_add_f32_e32 v154, v154, v38
	v_add_f32_e32 v155, v155, v39
	v_add_f32_e32 v154, v154, v22
	v_add_f32_e32 v155, v155, v23
	v_add_f32_e32 v154, v154, v6
	v_add_f32_e32 v155, v155, v7
	s_nop 0
	v_add_f32_dpp v154, v154, v154 quad_perm:[1,0,3,2] row_mask:0xf bank_mask:0xf
	v_add_f32_dpp v155, v155, v155 quad_perm:[1,0,3,2] row_mask:0xf bank_mask:0xf
	s_nop 0
	v_add_f32_dpp v154, v154, v154 quad_perm:[2,3,0,1] row_mask:0xf bank_mask:0xf
	v_add_f32_dpp v155, v155, v155 quad_perm:[2,3,0,1] row_mask:0xf bank_mask:0xf
	s_nop 0
	v_add_f32_dpp v154, v154, v154 row_half_mirror row_mask:0xf bank_mask:0xf
	v_add_f32_dpp v155, v155, v155 row_half_mirror row_mask:0xf bank_mask:0xf
	s_nop 0
	v_add_f32_dpp v154, v154, v154 row_mirror row_mask:0xf bank_mask:0xf
	v_add_f32_dpp v155, v155, v155 row_mirror row_mask:0xf bank_mask:0xf
	s_and_saveexec_b64 s[62:63], vcc
	global_store_dword v[148:149], v154, off offset:128
	s_bitset1_b32 s98, 8
	global_store_dword v[148:149], v155, off offset:132
	s_bitset1_b32 s98, 9
	s_or_b64 exec, exec, s[62:63]
	v_add_f32_e32 v154, 0, v120
	v_add_f32_e32 v155, 0, v121
	v_add_f32_e32 v154, v154, v104
	v_add_f32_e32 v155, v155, v105
	v_add_f32_e32 v154, v154, v88
	v_add_f32_e32 v155, v155, v89
	v_add_f32_e32 v154, v154, v72
	v_add_f32_e32 v155, v155, v73
	v_add_f32_e32 v154, v154, v56
	v_add_f32_e32 v155, v155, v57
	v_add_f32_e32 v154, v154, v40
	v_add_f32_e32 v155, v155, v41
	v_add_f32_e32 v154, v154, v24
	v_add_f32_e32 v155, v155, v25
	v_add_f32_e32 v154, v154, v8
	v_add_f32_e32 v155, v155, v9
	s_nop 0
	v_add_f32_dpp v154, v154, v154 quad_perm:[1,0,3,2] row_mask:0xf bank_mask:0xf
	v_add_f32_dpp v155, v155, v155 quad_perm:[1,0,3,2] row_mask:0xf bank_mask:0xf
	s_nop 0
	v_add_f32_dpp v154, v154, v154 quad_perm:[2,3,0,1] row_mask:0xf bank_mask:0xf
	v_add_f32_dpp v155, v155, v155 quad_perm:[2,3,0,1] row_mask:0xf bank_mask:0xf
	s_nop 0
	v_add_f32_dpp v154, v154, v154 row_half_mirror row_mask:0xf bank_mask:0xf
	v_add_f32_dpp v155, v155, v155 row_half_mirror row_mask:0xf bank_mask:0xf
	s_nop 0
	v_add_f32_dpp v154, v154, v154 row_mirror row_mask:0xf bank_mask:0xf
	v_add_f32_dpp v155, v155, v155 row_mirror row_mask:0xf bank_mask:0xf
	s_and_saveexec_b64 s[62:63], vcc
	global_store_dword v[148:149], v154, off offset:136
	s_bitset1_b32 s98, 10
	global_store_dword v[148:149], v155, off offset:140
	s_bitset1_b32 s98, 11
	s_or_b64 exec, exec, s[62:63]
	v_add_f32_e32 v154, 0, v114
	v_add_f32_e32 v155, 0, v115
	v_add_f32_e32 v154, v154, v98
	v_add_f32_e32 v155, v155, v99
	v_add_f32_e32 v154, v154, v82
	v_add_f32_e32 v155, v155, v83
	v_add_f32_e32 v154, v154, v66
	v_add_f32_e32 v155, v155, v67
	v_add_f32_e32 v154, v154, v50
	v_add_f32_e32 v155, v155, v51
	v_add_f32_e32 v154, v154, v34
	v_add_f32_e32 v155, v155, v35
	v_add_f32_e32 v154, v154, v18
	v_add_f32_e32 v155, v155, v19
	v_add_f32_e32 v154, v154, v2
	v_add_f32_e32 v155, v155, v3
	s_nop 0
	v_add_f32_dpp v154, v154, v154 quad_perm:[1,0,3,2] row_mask:0xf bank_mask:0xf
	v_add_f32_dpp v155, v155, v155 quad_perm:[1,0,3,2] row_mask:0xf bank_mask:0xf
	s_nop 0
	v_add_f32_dpp v154, v154, v154 quad_perm:[2,3,0,1] row_mask:0xf bank_mask:0xf
	v_add_f32_dpp v155, v155, v155 quad_perm:[2,3,0,1] row_mask:0xf bank_mask:0xf
	s_nop 0
	v_add_f32_dpp v154, v154, v154 row_half_mirror row_mask:0xf bank_mask:0xf
	v_add_f32_dpp v155, v155, v155 row_half_mirror row_mask:0xf bank_mask:0xf
	s_nop 0
	v_add_f32_dpp v154, v154, v154 row_mirror row_mask:0xf bank_mask:0xf
	v_add_f32_dpp v155, v155, v155 row_mirror row_mask:0xf bank_mask:0xf
	s_and_saveexec_b64 s[62:63], vcc
	global_store_dword v[148:149], v154, off offset:144
	s_bitset1_b32 s98, 12
	global_store_dword v[148:149], v155, off offset:148
	s_bitset1_b32 s98, 13
	s_or_b64 exec, exec, s[62:63]
	v_add_f32_e32 v154, 0, v116
	v_add_f32_e32 v155, 0, v117
	v_add_f32_e32 v154, v154, v100
	v_add_f32_e32 v155, v155, v101
	v_add_f32_e32 v154, v154, v84
	v_add_f32_e32 v155, v155, v85
	v_add_f32_e32 v154, v154, v68
	v_add_f32_e32 v155, v155, v69
	v_add_f32_e32 v154, v154, v52
	v_add_f32_e32 v155, v155, v53
	v_add_f32_e32 v154, v154, v36
	v_add_f32_e32 v155, v155, v37
	v_add_f32_e32 v154, v154, v20
	v_add_f32_e32 v155, v155, v21
	v_add_f32_e32 v154, v154, v4
	v_add_f32_e32 v155, v155, v5
	s_nop 0
	v_add_f32_dpp v154, v154, v154 quad_perm:[1,0,3,2] row_mask:0xf bank_mask:0xf
	v_add_f32_dpp v155, v155, v155 quad_perm:[1,0,3,2] row_mask:0xf bank_mask:0xf
	s_nop 0
	v_add_f32_dpp v154, v154, v154 quad_perm:[2,3,0,1] row_mask:0xf bank_mask:0xf
	v_add_f32_dpp v155, v155, v155 quad_perm:[2,3,0,1] row_mask:0xf bank_mask:0xf
	s_nop 0
	v_add_f32_dpp v154, v154, v154 row_half_mirror row_mask:0xf bank_mask:0xf
	v_add_f32_dpp v155, v155, v155 row_half_mirror row_mask:0xf bank_mask:0xf
	s_nop 0
	v_add_f32_dpp v154, v154, v154 row_mirror row_mask:0xf bank_mask:0xf
	v_add_f32_dpp v155, v155, v155 row_mirror row_mask:0xf bank_mask:0xf
	s_and_saveexec_b64 s[62:63], vcc
	global_store_dword v[148:149], v154, off offset:152
	s_bitset1_b32 s98, 14
	global_store_dword v[148:149], v155, off offset:156
	s_bitset1_b32 s98, 15
